# merge GEMM stagger: 4 XCD-pair groups, 5us steps (instead of 2 groups, 10us)
# baseline (speedup 1.0000x reference)
.LBB0_567:
	s_cmp_lt_i32 s76, 8
	s_cselect_b64 s[12:13], -1, 0
	s_cmp_gt_i32 s77, 7
	s_cselect_b64 s[4:5], -1, 0
	s_and_b64 s[4:5], s[12:13], s[4:5]
	s_andn2_b64 vcc, exec, s[4:5]
	v_bfe_u32 v223, v196, 2, 2
	s_cbranch_vccnz .LBB0_692
	s_cmpk_lt_i32 s2, 0x400
	s_cselect_b64 s[8:9], -1, 0
	s_cmpk_gt_i32 s2, 0x3ff
	s_mov_b64 s[6:7], s[0:1]
	v_readfirstlane_b32 s20, v196
	s_waitcnt vmcnt(0) lgkmcnt(0)
	s_barrier
	s_cbranch_scc1 .LBB0_570
	s_bfe_u32 s99, s2, 0x20001
	s_cmp_eq_u32 s99, 0
	s_cbranch_scc1 .Lstg7_done
.Lstg7_loop:
	s_sleep 127
	s_sleep 63
	s_sub_u32 s99, s99, 1
	s_cmp_lg_u32 s99, 0
	s_cbranch_scc1 .Lstg7_loop
